# issue-priority demotion: waves running a masked-tile skip variant drop to s_setprio 0 so the MFMA-issuing wave on the same SIMD wins arbitration
# speedup vs baseline: 1.0032x; 1.0032x over previous
; #define LAS __attribute__((address_space(3)))
; template <bool BAND> DI void partialSM(f32x16& p0, f32x16& p1, float& m_reg, float& mn, float& alpha, bool masked, const LAS float* tb, float C) {
;   if (masked) {
; #pragma unroll
;     for (int r = 0; r < 16; ++r) { p0[r] = -1e30f; p1[r] = -1e30f; }
; DI void finishSM(f32x16& p0, f32x16& p1, float alpha, float& l_reg, bf16x8& pa0, bf16x8& pa1, bf16x8& pa2, bf16x8& pa3) {
; #pragma unroll
;   for (int r = 0; r < 16; ++r) p1[r] = __builtin_amdgcn_exp2f(p1[r]);
;   float ps = 0;
; #pragma unroll
;   for (int r = 0; r < 16; ++r) ps += p0[r];
; #pragma unroll
;   for (int r = 0; r < 16; ++r) ps += p1[r];
;   { auto rr = __builtin_amdgcn_permlane32_swap(__float_as_uint(ps), __float_as_uint(ps), false, false);
;     ps = __uint_as_float(rr[0]) + __uint_as_float(rr[1]); }
;   l_reg = l_reg * alpha + ps;
;     ...
;   PK4(p0, 0, pa0); PK4(p0, 8, pa1); PK4(p1, 0, pa2); PK4(p1, 8, pa3);
.Lqsbb_skip:
	s_setprio 0
	v_exp_f32_e32 v200, v64
	v_add_f32_e32 v64, 0, v177
	v_add_f32_e32 v64, v179, v64
	v_add_f32_e32 v64, v175, v64
	v_add_f32_e32 v64, v178, v64
	v_add_f32_e32 v64, v174, v64
	v_add_f32_e32 v64, v176, v64
	v_add_f32_e32 v64, v172, v64
	v_add_f32_e32 v64, v173, v64
	v_add_f32_e32 v64, v169, v64
	v_add_f32_e32 v64, v171, v64
	v_add_f32_e32 v64, v168, v64
	v_add_f32_e32 v64, v170, v64
	v_exp_f32_e32 v78, v78
	v_add_f32_e32 v64, v165, v64
	v_exp_f32_e32 v79, v79
	v_add_f32_e32 v64, v167, v64
	v_exp_f32_e32 v76, v76
	v_add_f32_e32 v64, v164, v64
	v_exp_f32_e32 v77, v77
	v_add_f32_e32 v64, v166, v64
	v_exp_f32_e32 v74, v74
	v_add_f32_e32 v64, v78, v64
	v_exp_f32_e32 v75, v75
	v_add_f32_e32 v64, v79, v64
	v_add_f32_e32 v64, v76, v64
	v_add_f32_e32 v64, v77, v64
	v_add_f32_e32 v64, v74, v64
	v_add_f32_e32 v64, v75, v64
	v_exp_f32_e32 v201, v65
	v_exp_f32_e32 v192, v72
	v_exp_f32_e32 v193, v73
	v_exp_f32_e32 v194, v70
	v_exp_f32_e32 v195, v71
	v_add_f32_e32 v64, v192, v64
	v_add_f32_e32 v64, v193, v64
	v_add_f32_e32 v64, v194, v64
	v_exp_f32_e32 v196, v68
	v_exp_f32_e32 v197, v69
	v_exp_f32_e32 v198, v66
	v_exp_f32_e32 v199, v67
	v_add_f32_e32 v64, v195, v64
	v_add_f32_e32 v64, v196, v64
	v_add_f32_e32 v64, v197, v64
	v_add_f32_e32 v64, v198, v64
	v_add_f32_e32 v64, v199, v64
	v_add_f32_e32 v64, v200, v64
	v_add_f32_e32 v232, v201, v64
	v_mov_b32_e32 v233, v232
	v_cvt_pk_bf16_f32 v64, v177, v179
	v_cvt_pk_bf16_f32 v65, v175, v178
	v_cvt_pk_bf16_f32 v66, v174, v176
	v_cvt_pk_bf16_f32 v67, v172, v173
	v_cvt_pk_bf16_f32 v68, v169, v171
	v_cvt_pk_bf16_f32 v69, v168, v170
	v_cvt_pk_bf16_f32 v70, v165, v167
	v_cvt_pk_bf16_f32 v71, v164, v166
	v_cvt_pk_bf16_f32 v72, v78, v79
	v_cvt_pk_bf16_f32 v73, v76, v77
	v_cvt_pk_bf16_f32 v74, v74, v75
	v_cvt_pk_bf16_f32 v75, v192, v193
	v_cvt_pk_bf16_f32 v76, v194, v195
	v_cvt_pk_bf16_f32 v77, v196, v197
	v_cvt_pk_bf16_f32 v78, v198, v199
	v_cvt_pk_bf16_f32 v79, v200, v201
	s_nop 1
	v_permlane32_swap_b32_e32 v232, v233
	v_permlane32_swap_b32_e32 v64, v66
	v_permlane32_swap_b32_e32 v65, v67
	v_permlane32_swap_b32_e32 v68, v70
	v_permlane32_swap_b32_e32 v69, v71
	v_permlane32_swap_b32_e32 v72, v74
	v_permlane32_swap_b32_e32 v73, v75
	v_permlane32_swap_b32_e32 v76, v78
	v_permlane32_swap_b32_e32 v77, v79
	s_setprio 1
	s_branch .Lqsbb_join
.Lqsba_skip:
	s_setprio 0
	v_exp_f32_e32 v192, v200
	v_exp_f32_e32 v200, v212
	v_add_f32_e32 v212, 0, v96
	v_add_f32_e32 v212, v111, v212
	v_add_f32_e32 v212, v97, v212
	v_add_f32_e32 v212, v110, v212
	v_add_f32_e32 v212, v98, v212
	v_add_f32_e32 v212, v109, v212
	v_add_f32_e32 v212, v99, v212
	v_add_f32_e32 v212, v108, v212
	v_add_f32_e32 v212, v100, v212
	v_add_f32_e32 v212, v107, v212
	v_add_f32_e32 v212, v101, v212
	v_add_f32_e32 v212, v106, v212
	v_add_f32_e32 v212, v102, v212
	v_exp_f32_e32 v193, v201
	v_add_f32_e32 v212, v105, v212
	v_exp_f32_e32 v194, v202
	v_add_f32_e32 v212, v103, v212
	v_exp_f32_e32 v195, v203
	v_add_f32_e32 v212, v104, v212
	v_exp_f32_e32 v196, v204
	v_add_f32_e32 v212, v192, v212
	v_exp_f32_e32 v197, v205
	v_add_f32_e32 v212, v193, v212
	v_exp_f32_e32 v198, v206
	v_add_f32_e32 v212, v194, v212
	v_exp_f32_e32 v199, v207
	v_add_f32_e32 v212, v195, v212
	v_add_f32_e32 v212, v196, v212
	v_exp_f32_e32 v201, v213
	v_add_f32_e32 v212, v197, v212
	v_exp_f32_e32 v202, v214
	v_add_f32_e32 v212, v198, v212
	v_exp_f32_e32 v203, v215
	v_add_f32_e32 v212, v199, v212
	v_exp_f32_e32 v204, v234
	v_add_f32_e32 v212, v200, v212
	v_exp_f32_e32 v205, v236
	v_add_f32_e32 v212, v201, v212
	v_exp_f32_e32 v206, v237
	v_add_f32_e32 v212, v202, v212
	v_exp_f32_e32 v207, v242
	v_add_f32_e32 v212, v203, v212
	v_add_f32_e32 v212, v204, v212
	v_add_f32_e32 v212, v205, v212
	v_add_f32_e32 v212, v206, v212
	v_add_f32_e32 v236, v207, v212
	v_mov_b32_e32 v237, v236
	v_cvt_pk_bf16_f32 v96, v96, v111
	v_cvt_pk_bf16_f32 v97, v97, v110
	v_cvt_pk_bf16_f32 v98, v98, v109
	v_cvt_pk_bf16_f32 v99, v99, v108
	v_cvt_pk_bf16_f32 v100, v100, v107
	v_cvt_pk_bf16_f32 v101, v101, v106
	v_cvt_pk_bf16_f32 v102, v102, v105
	v_cvt_pk_bf16_f32 v103, v103, v104
	v_cvt_pk_bf16_f32 v104, v192, v193
	v_cvt_pk_bf16_f32 v105, v194, v195
	v_cvt_pk_bf16_f32 v106, v196, v197
	v_cvt_pk_bf16_f32 v107, v198, v199
	v_cvt_pk_bf16_f32 v108, v200, v201
	v_cvt_pk_bf16_f32 v109, v202, v203
	v_cvt_pk_bf16_f32 v110, v204, v205
	v_cvt_pk_bf16_f32 v111, v206, v207
	s_nop 1
	v_permlane32_swap_b32_e32 v236, v237
	v_permlane32_swap_b32_e32 v96, v98
	v_permlane32_swap_b32_e32 v97, v99
	v_permlane32_swap_b32_e32 v100, v102
	v_permlane32_swap_b32_e32 v101, v103
	v_permlane32_swap_b32_e32 v104, v106
	v_permlane32_swap_b32_e32 v105, v107
	v_permlane32_swap_b32_e32 v108, v110
	v_permlane32_swap_b32_e32 v109, v111
	s_setprio 1
	s_branch .Lqsba_join
.Lpvbb_skip:
	s_setprio 0
	s_nop 0
	s_cmp_gt_i32 s34, s18
	s_cselect_b64 s[16:17], -1, 0
	s_cmp_gt_i32 s18, s25
	s_cselect_b64 s[22:23], -1, 0
	s_or_b64 s[16:17], s[16:17], s[22:23]
	s_and_b64 vcc, exec, s[16:17]
	v_mov_b32_e32 v64, 0xf149f2ca
	v_mov_b32_e32 v68, 0xf149f2ca
	v_mov_b32_e32 v69, 0xf149f2ca
	v_mov_b32_e32 v70, 0xf149f2ca
	v_mov_b32_e32 v71, 0xf149f2ca
	v_mov_b32_e32 v65, 0xf149f2ca
	v_mov_b32_e32 v66, 0xf149f2ca
	v_mov_b32_e32 v67, 0xf149f2ca
	v_mov_b32_e32 v72, 0xf149f2ca
	v_mov_b32_e32 v73, 0xf149f2ca
	v_mov_b32_e32 v74, 0xf149f2ca
	v_mov_b32_e32 v75, 0xf149f2ca
	v_mov_b32_e32 v200, 0xf149f2ca
	v_mov_b32_e32 v201, 0xf149f2ca
	v_mov_b32_e32 v202, 0xf149f2ca
	v_mov_b32_e32 v78, 0xf149f2ca
	v_mov_b32_e32 v79, 0xf149f2ca
	v_mov_b32_e32 v76, 0xf149f2ca
	v_mov_b32_e32 v77, 0xf149f2ca
	v_mov_b32_e32 v206, 0xf149f2ca
	v_mov_b32_e32 v207, 0xf149f2ca
	v_mov_b32_e32 v204, 0xf149f2ca
	v_mov_b32_e32 v205, 0xf149f2ca
	v_mov_b32_e32 v203, 0xf149f2ca
	v_mov_b32_e32 v198, 0xf149f2ca
	v_mov_b32_e32 v199, 0xf149f2ca
	v_mov_b32_e32 v196, 0xf149f2ca
	v_mov_b32_e32 v197, 0xf149f2ca
	v_mov_b32_e32 v194, 0xf149f2ca
	v_mov_b32_e32 v195, 0xf149f2ca
	v_mov_b32_e32 v192, 0xf149f2ca
	v_mov_b32_e32 v193, 0xf149f2ca
	s_setprio 1
	s_branch .Lpvbb_join
; #define LAS __attribute__((address_space(3)))
; #define SBAR() __builtin_amdgcn_sched_barrier(0)
; #define RESC(a) do { if (__any((a) < 1.f)) { if (hi == 0) al_l[r32] = (a); asm volatile("s_waitcnt lgkmcnt(0)" ::: "memory"); \
;     _Pragma("unroll") for (int d = 0; d < 4; ++d) _Pragma("unroll") for (int r = 0; r < 16; ++r) o[d][r] *= al_l[crow(r, hi)]; } } while (0)
; template <bool BAND> DI void partialSM(f32x16& p0, f32x16& p1, float& m_reg, float& mn, float& alpha, bool masked, const LAS float* tb, float C) {
;   if (masked) {
; #pragma unroll
;     for (int r = 0; r < 16; ++r) { p0[r] = -1e30f; p1[r] = -1e30f; }
; template <bool BAND, int SD, bool ACT> DI void attn_unit_(const Unit& U, LAS char* lds, float C) {
;     ...
;   if (ACT) {
;     qkt<NQ>(pB0, pB1, K_lds + SHM_K, KR_lds + SHM_KR, qr, r32, hi);
;     finishSM(pA0, pA1, alA, l_reg, pa0, pa1, pa2, pa3); SBAR();
;     pv_d0(o, vb0, pa0, pa1, pa2, pa3); partialSM<BAND>(pB0, pB1, m_reg, mnB, alB, MASKED(NT - 1), T3 + jb0 + 64 * (NT - 1), C);
;   }
;   __syncthreads();
;   if (ACT) {
;     RESC(alB);
;     finishSM(pB0, pB1, alB, l_reg, pa0, pa1, pa2, pa3); SBAR();
;     pv_d0(o, vb0 + SHM_V, pa0, pa1, pa2, pa3);
;     if (hi == 0) li_l[r32] = l_reg; asm volatile("s_waitcnt lgkmcnt(0)" ::: "memory");
.Lpvba_skip:
	s_setprio 0
	s_nop 0
	s_cmp_gt_i32 s34, s19
	s_cselect_b64 s[22:23], -1, 0
	s_cmp_ge_i32 s18, s25
	s_cselect_b64 s[18:19], -1, 0
	s_or_b64 s[18:19], s[22:23], s[18:19]
	v_mov_b32_e32 v96, 0xf149f2ca
	s_and_b64 vcc, exec, s[18:19]
	v_mov_b32_e32 v97, 0xf149f2ca
	v_mov_b32_e32 v98, 0xf149f2ca
	v_mov_b32_e32 v99, 0xf149f2ca
	v_mov_b32_e32 v100, 0xf149f2ca
	v_mov_b32_e32 v101, 0xf149f2ca
	v_mov_b32_e32 v102, 0xf149f2ca
	v_mov_b32_e32 v103, 0xf149f2ca
	v_mov_b32_e32 v104, 0xf149f2ca
	v_mov_b32_e32 v105, 0xf149f2ca
	v_mov_b32_e32 v106, 0xf149f2ca
	v_mov_b32_e32 v107, 0xf149f2ca
	v_mov_b32_e32 v200, 0xf149f2ca
	v_mov_b32_e32 v201, 0xf149f2ca
	v_mov_b32_e32 v202, 0xf149f2ca
	v_mov_b32_e32 v108, 0xf149f2ca
	v_mov_b32_e32 v109, 0xf149f2ca
	v_mov_b32_e32 v110, 0xf149f2ca
	v_mov_b32_e32 v111, 0xf149f2ca
	v_mov_b32_e32 v206, 0xf149f2ca
	v_mov_b32_e32 v207, 0xf149f2ca
	v_mov_b32_e32 v204, 0xf149f2ca
	v_mov_b32_e32 v205, 0xf149f2ca
	v_mov_b32_e32 v203, 0xf149f2ca
	v_mov_b32_e32 v198, 0xf149f2ca
	v_mov_b32_e32 v199, 0xf149f2ca
	v_mov_b32_e32 v196, 0xf149f2ca
	v_mov_b32_e32 v197, 0xf149f2ca
	v_mov_b32_e32 v194, 0xf149f2ca
	v_mov_b32_e32 v195, 0xf149f2ca
	v_mov_b32_e32 v192, 0xf149f2ca
	v_mov_b32_e32 v193, 0xf149f2ca
	s_setprio 1
	s_branch .Lpvba_join
.Lqsbp_skip:
	s_setprio 0
	s_waitcnt lgkmcnt(0)
	s_ashr_i32 s25, s42, 7
	s_add_i32 s34, s25, s41
	s_cmp_gt_i32 s34, 0
	s_cselect_b64 s[18:19], -1, 0
	s_add_i32 s25, s25, s40
	s_cmp_lt_i32 s25, 0
	s_cselect_b64 s[22:23], -1, 0
	s_or_b64 s[18:19], s[18:19], s[22:23]
	v_readlane_b32 s20, v254, 62
	s_and_b64 vcc, exec, s[18:19]
	v_mov_b32_e32 v74, 0xf149f2ca
	v_lshl_add_u32 v221, v56, 2, s20
	v_mov_b32_e32 v75, 0xf149f2ca
	v_mov_b32_e32 v72, 0xf149f2ca
	v_mov_b32_e32 v73, 0xf149f2ca
	v_mov_b32_e32 v70, 0xf149f2ca
	v_mov_b32_e32 v71, 0xf149f2ca
	v_mov_b32_e32 v68, 0xf149f2ca
	v_mov_b32_e32 v69, 0xf149f2ca
	v_mov_b32_e32 v76, 0xf149f2ca
	v_mov_b32_e32 v77, 0xf149f2ca
	v_mov_b32_e32 v78, 0xf149f2ca
	v_mov_b32_e32 v79, 0xf149f2ca
	v_mov_b32_e32 v64, 0xf149f2ca
	v_mov_b32_e32 v65, 0xf149f2ca
	v_mov_b32_e32 v66, 0xf149f2ca
	v_mov_b32_e32 v67, 0xf149f2ca
	v_mov_b32_e32 v62, 0xf149f2ca
	v_mov_b32_e32 v63, 0xf149f2ca
	v_mov_b32_e32 v60, 0xf149f2ca
	v_mov_b32_e32 v61, 0xf149f2ca
	v_mov_b32_e32 v56, 0xf149f2ca
	v_mov_b32_e32 v57, 0xf149f2ca
	v_mov_b32_e32 v58, 0xf149f2ca
	v_mov_b32_e32 v59, 0xf149f2ca
	v_mov_b32_e32 v48, 0xf149f2ca
	v_mov_b32_e32 v49, 0xf149f2ca
	v_mov_b32_e32 v50, 0xf149f2ca
	v_mov_b32_e32 v51, 0xf149f2ca
	v_mov_b32_e32 v54, 0xf149f2ca
	v_mov_b32_e32 v55, 0xf149f2ca
	v_mov_b32_e32 v52, 0xf149f2ca
	v_mov_b32_e32 v53, 0xf149f2ca
	s_setprio 1
	s_branch .Lqsbp_join
.Lqsbe_skip:
	s_setprio 0
	s_waitcnt lgkmcnt(0)
	v_exp_f32_e32 v110, v78
	v_exp_f32_e32 v111, v79
	v_exp_f32_e32 v114, v76
	v_exp_f32_e32 v115, v77
	v_exp_f32_e32 v212, v74
	v_exp_f32_e32 v213, v75
	v_exp_f32_e32 v72, v72
	v_exp_f32_e32 v73, v73
	v_exp_f32_e32 v214, v70
	v_exp_f32_e32 v215, v71
	v_exp_f32_e32 v224, v69
	v_exp_f32_e32 v222, v68
	v_exp_f32_e32 v138, v64
	v_add_f32_e32 v64, 0, v177
	v_add_f32_e32 v64, v179, v64
	v_add_f32_e32 v64, v175, v64
	v_add_f32_e32 v64, v178, v64
	v_add_f32_e32 v64, v174, v64
	v_add_f32_e32 v64, v176, v64
	v_add_f32_e32 v64, v172, v64
	v_add_f32_e32 v64, v173, v64
	v_add_f32_e32 v64, v169, v64
	v_add_f32_e32 v64, v171, v64
	v_add_f32_e32 v64, v168, v64
	v_add_f32_e32 v64, v170, v64
	v_add_f32_e32 v64, v165, v64
	v_add_f32_e32 v64, v167, v64
	v_add_f32_e32 v64, v164, v64
	v_add_f32_e32 v64, v166, v64
	v_add_f32_e32 v64, v110, v64
	v_add_f32_e32 v64, v111, v64
	v_add_f32_e32 v64, v114, v64
	v_add_f32_e32 v64, v115, v64
	v_add_f32_e32 v64, v212, v64
	v_add_f32_e32 v64, v213, v64
	v_add_f32_e32 v64, v72, v64
	v_add_f32_e32 v64, v73, v64
	v_exp_f32_e32 v136, v66
	v_add_f32_e32 v64, v214, v64
	v_exp_f32_e32 v137, v67
	v_add_f32_e32 v64, v215, v64
	v_add_f32_e32 v64, v222, v64
	v_exp_f32_e32 v139, v65
	v_add_f32_e32 v64, v224, v64
	v_add_f32_e32 v64, v136, v64
	v_add_f32_e32 v64, v137, v64
	v_add_f32_e32 v64, v138, v64
	v_add_f32_e32 v112, v139, v64
	v_mov_b32_e32 v130, v112
	v_cvt_pk_bf16_f32 v64, v177, v179
	v_cvt_pk_bf16_f32 v65, v175, v178
	v_cvt_pk_bf16_f32 v66, v174, v176
	v_cvt_pk_bf16_f32 v67, v172, v173
	v_cvt_pk_bf16_f32 v68, v169, v171
	v_cvt_pk_bf16_f32 v69, v168, v170
	v_cvt_pk_bf16_f32 v70, v165, v167
	v_cvt_pk_bf16_f32 v71, v164, v166
	v_cvt_pk_bf16_f32 v124, v110, v111
	v_cvt_pk_bf16_f32 v125, v114, v115
	v_cvt_pk_bf16_f32 v126, v212, v213
	v_cvt_pk_bf16_f32 v127, v72, v73
	v_permlane32_swap_b32_e32 v112, v130
	v_permlane32_swap_b32_e32 v64, v66
	v_permlane32_swap_b32_e32 v65, v67
	v_permlane32_swap_b32_e32 v68, v70
	v_permlane32_swap_b32_e32 v69, v71
	v_permlane32_swap_b32_e32 v124, v126
	v_permlane32_swap_b32_e32 v125, v127
	v_cvt_pk_bf16_f32 v132, v214, v215
	v_cvt_pk_bf16_f32 v133, v222, v224
	v_cvt_pk_bf16_f32 v134, v136, v137
	v_cvt_pk_bf16_f32 v135, v138, v139
	s_nop 0
	v_permlane32_swap_b32_e32 v132, v134
	v_permlane32_swap_b32_e32 v133, v135
	s_setprio 1
	s_branch .Lqsbe_join
.Lpvbe_skip:
	s_setprio 0
	s_waitcnt lgkmcnt(0)
	s_nop 0
	s_add_i32 s13, s21, -1
	s_cmp_le_i32 s21, s12
	s_cselect_b64 s[14:15], -1, 0
	s_cmp_gt_i32 s13, s25
	s_cselect_b64 s[16:17], -1, 0
	s_or_b64 s[14:15], s[14:15], s[16:17]
	v_mov_b32_e32 v118, 0xf149f2ca
	s_and_b64 vcc, exec, s[14:15]
	v_mov_b32_e32 v119, 0xf149f2ca
	v_mov_b32_e32 v120, 0xf149f2ca
	v_mov_b32_e32 v121, 0xf149f2ca
	v_mov_b32_e32 v114, 0xf149f2ca
	v_mov_b32_e32 v115, 0xf149f2ca
	v_mov_b32_e32 v110, 0xf149f2ca
	v_mov_b32_e32 v111, 0xf149f2ca
	v_mov_b32_e32 v106, 0xf149f2ca
	v_mov_b32_e32 v107, 0xf149f2ca
	v_mov_b32_e32 v70, 0xf149f2ca
	v_mov_b32_e32 v71, 0xf149f2ca
	v_mov_b32_e32 v66, 0xf149f2ca
	v_mov_b32_e32 v67, 0xf149f2ca
	v_mov_b32_e32 v64, 0xf149f2ca
	v_mov_b32_e32 v65, 0xf149f2ca
	v_mov_b32_e32 v128, 0xf149f2ca
	v_mov_b32_e32 v129, 0xf149f2ca
	v_mov_b32_e32 v126, 0xf149f2ca
	v_mov_b32_e32 v127, 0xf149f2ca
	v_mov_b32_e32 v124, 0xf149f2ca
	v_mov_b32_e32 v125, 0xf149f2ca
	v_mov_b32_e32 v122, 0xf149f2ca
	v_mov_b32_e32 v123, 0xf149f2ca
	v_mov_b32_e32 v116, 0xf149f2ca
	v_mov_b32_e32 v117, 0xf149f2ca
	v_mov_b32_e32 v108, 0xf149f2ca
	v_mov_b32_e32 v109, 0xf149f2ca
	v_mov_b32_e32 v72, 0xf149f2ca
	v_mov_b32_e32 v73, 0xf149f2ca
	v_mov_b32_e32 v68, 0xf149f2ca
	v_mov_b32_e32 v69, 0xf149f2ca
	s_setprio 1
	s_branch .Lpvbe_join
.Lpvbf_skip:
	s_setprio 0
	s_waitcnt lgkmcnt(0)
	s_add_i32 s12, 0, 0x4000
	v_add_u32_e32 v75, s12, v219
	s_nop 0
	v_cmp_gt_u32_e32 vcc, 32, v191
	s_setprio 1
	s_branch .Lpvbf_join

; DI void finishSM(f32x16& p0, f32x16& p1, float alpha, float& l_reg, bf16x8& pa0, bf16x8& pa1, bf16x8& pa2, bf16x8& pa3) {
; #pragma unroll
;   for (int r = 0; r < 16; ++r) p1[r] = __builtin_amdgcn_exp2f(p1[r]);
;   float ps = 0;
; #pragma unroll
;   for (int r = 0; r < 16; ++r) ps += p0[r];
; #pragma unroll
;   for (int r = 0; r < 16; ++r) ps += p1[r];
;   { auto rr = __builtin_amdgcn_permlane32_swap(__float_as_uint(ps), __float_as_uint(ps), false, false);
;     ps = __uint_as_float(rr[0]) + __uint_as_float(rr[1]); }
;   l_reg = l_reg * alpha + ps;
;     ...
;   PK4(p0, 0, pa0); PK4(p0, 8, pa1); PK4(p1, 0, pa2); PK4(p1, 8, pa3);
.Lqsmb_skip:
	s_setprio 0
	v_exp_f32_e32 v170, v170
	v_exp_f32_e32 v171, v171
	v_exp_f32_e32 v168, v168
	v_exp_f32_e32 v169, v169
	v_exp_f32_e32 v222, v174
	v_exp_f32_e32 v174, v164
	v_add_f32_e32 v164, 0, v110
	v_add_f32_e32 v164, v111, v164
	v_add_f32_e32 v164, v108, v164
	v_add_f32_e32 v164, v109, v164
	v_add_f32_e32 v164, v106, v164
	v_add_f32_e32 v164, v107, v164
	v_add_f32_e32 v164, v72, v164
	v_add_f32_e32 v164, v73, v164
	v_add_f32_e32 v164, v66, v164
	v_add_f32_e32 v164, v67, v164
	v_add_f32_e32 v164, v64, v164
	v_add_f32_e32 v164, v65, v164
	v_exp_f32_e32 v225, v196
	v_add_f32_e32 v164, v68, v164
	v_exp_f32_e32 v227, v197
	v_add_f32_e32 v164, v69, v164
	v_exp_f32_e32 v196, v178
	v_add_f32_e32 v164, v70, v164
	v_exp_f32_e32 v197, v179
	v_add_f32_e32 v164, v71, v164
	v_add_f32_e32 v164, v225, v164
	v_exp_f32_e32 v223, v175
	v_add_f32_e32 v164, v227, v164
	v_exp_f32_e32 v224, v172
	v_add_f32_e32 v164, v196, v164
	v_exp_f32_e32 v226, v173
	v_add_f32_e32 v164, v197, v164
	v_add_f32_e32 v164, v222, v164
	v_add_f32_e32 v164, v223, v164
	v_add_f32_e32 v164, v224, v164
	v_add_f32_e32 v164, v226, v164
	v_exp_f32_e32 v172, v166
	v_add_f32_e32 v164, v170, v164
	v_exp_f32_e32 v173, v167
	v_add_f32_e32 v164, v171, v164
	v_add_f32_e32 v164, v168, v164
	v_exp_f32_e32 v175, v165
	v_add_f32_e32 v164, v169, v164
	v_add_f32_e32 v164, v172, v164
	v_add_f32_e32 v164, v173, v164
	v_add_f32_e32 v164, v174, v164
	v_add_f32_e32 v220, v175, v164
	v_mov_b32_e32 v221, v220
	v_cvt_pk_bf16_f32 v164, v110, v111
	v_cvt_pk_bf16_f32 v165, v108, v109
	v_cvt_pk_bf16_f32 v166, v106, v107
	v_cvt_pk_bf16_f32 v167, v72, v73
	v_cvt_pk_bf16_f32 v176, v66, v67
	v_cvt_pk_bf16_f32 v177, v64, v65
	v_cvt_pk_bf16_f32 v178, v68, v69
	v_cvt_pk_bf16_f32 v179, v70, v71
	v_cvt_pk_bf16_f32 v228, v225, v227
	v_cvt_pk_bf16_f32 v229, v196, v197
	v_cvt_pk_bf16_f32 v230, v222, v223
	v_cvt_pk_bf16_f32 v231, v224, v226
	v_cvt_pk_bf16_f32 v222, v170, v171
	v_cvt_pk_bf16_f32 v223, v168, v169
	v_cvt_pk_bf16_f32 v224, v172, v173
	s_nop 1
	v_permlane32_swap_b32_e32 v220, v221
	v_cvt_pk_bf16_f32 v225, v174, v175
	v_permlane32_swap_b32_e32 v222, v224
	v_permlane32_swap_b32_e32 v164, v166
	v_permlane32_swap_b32_e32 v165, v167
	v_permlane32_swap_b32_e32 v176, v178
	v_permlane32_swap_b32_e32 v177, v179
	v_permlane32_swap_b32_e32 v228, v230
	v_permlane32_swap_b32_e32 v229, v231
	v_permlane32_swap_b32_e32 v223, v225
	s_setprio 1
	s_branch .Lqsmb_join
.Lqsma_skip:
	s_setprio 0
	v_exp_f32_e32 v177, v177
	v_exp_f32_e32 v179, v179
	v_exp_f32_e32 v166, v166
	v_exp_f32_e32 v167, v167
	v_exp_f32_e32 v165, v165
	v_exp_f32_e32 v102, v102
	v_exp_f32_e32 v196, v196
	v_exp_f32_e32 v197, v197
	v_exp_f32_e32 v228, v172
	v_exp_f32_e32 v215, v168
	v_add_f32_e32 v168, 0, v110
	v_add_f32_e32 v168, v164, v168
	v_add_f32_e32 v168, v108, v168
	v_add_f32_e32 v168, v111, v168
	v_add_f32_e32 v168, v107, v168
	v_add_f32_e32 v168, v109, v168
	v_add_f32_e32 v168, v105, v168
	v_add_f32_e32 v168, v106, v168
	v_add_f32_e32 v168, v101, v168
	v_add_f32_e32 v168, v104, v168
	v_add_f32_e32 v168, v100, v168
	v_add_f32_e32 v168, v103, v168
	v_exp_f32_e32 v212, v173
	v_add_f32_e32 v168, v97, v168
	v_exp_f32_e32 v213, v174
	v_add_f32_e32 v168, v99, v168
	v_exp_f32_e32 v214, v175
	v_add_f32_e32 v168, v96, v168
	v_add_f32_e32 v168, v98, v168
	v_add_f32_e32 v168, v212, v168
	v_add_f32_e32 v168, v213, v168
	v_add_f32_e32 v168, v214, v168
	v_add_f32_e32 v168, v177, v168
	v_exp_f32_e32 v225, v169
	v_add_f32_e32 v168, v179, v168
	v_exp_f32_e32 v226, v170
	v_add_f32_e32 v168, v166, v168
	v_exp_f32_e32 v227, v171
	v_add_f32_e32 v168, v167, v168
	v_add_f32_e32 v168, v215, v168
	v_add_f32_e32 v168, v225, v168
	v_add_f32_e32 v168, v226, v168
	v_add_f32_e32 v168, v227, v168
	v_add_f32_e32 v168, v228, v168
	v_add_f32_e32 v168, v165, v168
	v_add_f32_e32 v168, v102, v168
	v_add_f32_e32 v168, v196, v168
	v_add_f32_e32 v223, v197, v168
	v_mov_b32_e32 v224, v223
	v_cvt_pk_bf16_f32 v168, v110, v164
	v_cvt_pk_bf16_f32 v169, v108, v111
	v_cvt_pk_bf16_f32 v170, v107, v109
	s_nop 1
	v_permlane32_swap_b32_e32 v223, v224
	v_cvt_pk_bf16_f32 v171, v105, v106
	v_permlane32_swap_b32_e32 v168, v170
	v_cvt_pk_bf16_f32 v172, v101, v104
	v_cvt_pk_bf16_f32 v173, v100, v103
	v_cvt_pk_bf16_f32 v174, v97, v99
	v_cvt_pk_bf16_f32 v175, v96, v98
	v_cvt_pk_bf16_f32 v212, v212, v213
	v_cvt_pk_bf16_f32 v213, v214, v177
	v_cvt_pk_bf16_f32 v214, v179, v166
	v_cvt_pk_bf16_f32 v215, v167, v215
	v_cvt_pk_bf16_f32 v226, v225, v226
	v_cvt_pk_bf16_f32 v227, v227, v228
	v_cvt_pk_bf16_f32 v228, v165, v102
	v_cvt_pk_bf16_f32 v229, v196, v197
	v_permlane32_swap_b32_e32 v169, v171
	v_permlane32_swap_b32_e32 v172, v174
	v_permlane32_swap_b32_e32 v173, v175
	v_permlane32_swap_b32_e32 v212, v214
	v_permlane32_swap_b32_e32 v213, v215
	v_permlane32_swap_b32_e32 v226, v228
	v_permlane32_swap_b32_e32 v227, v229
	s_setprio 1
	s_branch .Lqsma_join
; #define LAS __attribute__((address_space(3)))
; #define SBAR() __builtin_amdgcn_sched_barrier(0)
; template <bool BAND> DI void partialSM(f32x16& p0, f32x16& p1, float& m_reg, float& mn, float& alpha, bool masked, const LAS float* tb, float C) {
;   if (masked) {
; #pragma unroll
;     for (int r = 0; r < 16; ++r) { p0[r] = -1e30f; p1[r] = -1e30f; }
;   } else if (BAND) {
; #pragma unroll
;     for (int r = 0; r < 16; ++r) { const int ko = (r & 3) + 8 * (r >> 2); p0[r] = fmaf(p0[r], C, tb[ko]); }
;     SBAR();
; #pragma unroll
;     for (int r = 0; r < 16; ++r) { const int ko = (r & 3) + 8 * (r >> 2); p1[r] = fmaf(p1[r], C, tb[ko + 32]); }
;   }
;   const float CC = BAND ? 1.f : C;
;   const float THRP = 11.5f / CC;
;   float pmax = p0[0];
; #pragma unroll
;   for (int r = 1; r < 16; ++r) pmax = fmaxf(pmax, p0[r]);
; #pragma unroll
;   for (int r = 0; r < 16; ++r) pmax = fmaxf(pmax, p1[r]);
;   { auto rr = __builtin_amdgcn_permlane32_swap(__float_as_uint(pmax), __float_as_uint(pmax), false, false);
;     pmax = fmaxf(__uint_as_float(rr[0]), __uint_as_float(rr[1])); }
;   if (__builtin_expect(__all(pmax - m_reg <= THRP), 1)) { mn = m_reg; alpha = 1.f; }
;   else { mn = fmaxf(m_reg, pmax); alpha = __builtin_amdgcn_exp2f((m_reg - mn) * CC); m_reg = mn; }
.Lpvmb_skip:
	s_setprio 0
	s_nop 0
	s_nop 0
	s_cmp_gt_i32 s34, s37
	s_cselect_b64 s[16:17], -1, 0
	s_cmp_gt_i32 s37, s21
	s_cselect_b64 s[22:23], -1, 0
	s_or_b64 vcc, s[16:17], s[22:23]
	v_cndmask_b32_e32 v74, v74, v211, vcc
	v_cndmask_b32_e32 v75, v75, v211, vcc
	v_cndmask_b32_e32 v72, v104, v211, vcc
	v_cndmask_b32_e32 v73, v105, v211, vcc
	v_cndmask_b32_e32 v104, v102, v211, vcc
	v_cndmask_b32_e32 v102, v103, v211, vcc
	v_max_f32_e32 v103, v75, v75
	v_max_f32_e32 v105, v74, v74
	v_cndmask_b32_e32 v76, v76, v211, vcc
	v_cndmask_b32_e32 v77, v77, v211, vcc
	v_max_f32_e32 v103, v105, v103
	v_cndmask_b32_e32 v78, v78, v211, vcc
	v_cndmask_b32_e32 v79, v79, v211, vcc
	v_max3_f32 v103, v103, v76, v77
	v_cndmask_b32_e32 v80, v80, v211, vcc
	v_cndmask_b32_e32 v81, v81, v211, vcc
	v_max3_f32 v103, v103, v78, v79
	v_cndmask_b32_e32 v82, v82, v211, vcc
	v_cndmask_b32_e32 v83, v83, v211, vcc
	v_max3_f32 v103, v103, v80, v81
	v_cndmask_b32_e32 v84, v84, v211, vcc
	v_cndmask_b32_e32 v85, v85, v211, vcc
	v_max3_f32 v103, v103, v82, v83
	v_cndmask_b32_e32 v86, v86, v211, vcc
	v_cndmask_b32_e32 v87, v87, v211, vcc
	v_max3_f32 v103, v103, v84, v85
	v_cndmask_b32_e32 v88, v88, v211, vcc
	v_cndmask_b32_e32 v89, v89, v211, vcc
	v_max3_f32 v103, v103, v86, v87
	v_cndmask_b32_e32 v90, v90, v211, vcc
	v_cndmask_b32_e32 v91, v91, v211, vcc
	v_max3_f32 v103, v103, v88, v89
	v_cndmask_b32_e32 v92, v92, v211, vcc
	v_cndmask_b32_e32 v93, v93, v211, vcc
	v_max3_f32 v103, v103, v90, v91
	v_cndmask_b32_e32 v94, v94, v211, vcc
	v_cndmask_b32_e32 v95, v95, v211, vcc
	v_max3_f32 v103, v103, v92, v93
	v_cndmask_b32_e32 v96, v96, v211, vcc
	v_cndmask_b32_e32 v97, v97, v211, vcc
	v_max3_f32 v103, v103, v94, v95
	v_cndmask_b32_e32 v98, v98, v211, vcc
	v_cndmask_b32_e32 v99, v99, v211, vcc
	v_max3_f32 v103, v103, v96, v97
	v_cndmask_b32_e32 v100, v100, v211, vcc
	v_cndmask_b32_e32 v101, v101, v211, vcc
	v_max3_f32 v103, v103, v98, v99
	v_max3_f32 v103, v103, v100, v101
	v_max3_f32 v103, v103, v104, v102
	v_max3_f32 v103, v103, v72, v73
	v_mov_b32_e32 v105, v103
	s_nop 1
	v_permlane32_swap_b32_e32 v103, v105
	v_max_f32_e32 v105, v105, v105
	v_max_f32_e32 v103, v103, v103
	v_max_f32_e32 v103, v103, v105
	v_sub_f32_e32 v105, v103, v203
	v_cmp_ge_f32_e32 vcc, s84, v105
	v_mov_b32_e32 v222, 1.0
	s_cmp_eq_u64 vcc, exec
	s_setprio 1
	s_branch .Lpvmb_join
.Lpvma_skip:
	s_setprio 0
	s_nop 0
	s_cmp_gt_i32 s34, s39
	s_cselect_b64 s[16:17], -1, 0
	s_cmp_ge_i32 s37, s21
	s_cselect_b64 s[22:23], -1, 0
	s_or_b64 vcc, s[16:17], s[22:23]
	v_cndmask_b32_e32 v65, v65, v211, vcc
	v_cndmask_b32_e32 v64, v64, v211, vcc
	v_max_f32_e32 v168, v65, v65
	v_max_f32_e32 v169, v64, v64
	v_cndmask_b32_e32 v67, v67, v211, vcc
	v_cndmask_b32_e32 v66, v66, v211, vcc
	v_max_f32_e32 v168, v169, v168
	v_cndmask_b32_e32 v69, v69, v211, vcc
	v_cndmask_b32_e32 v68, v68, v211, vcc
	v_max3_f32 v168, v168, v66, v67
	v_cndmask_b32_e32 v71, v71, v211, vcc
	v_cndmask_b32_e32 v70, v70, v211, vcc
	v_max3_f32 v168, v168, v68, v69
	v_cndmask_b32_e32 v73, v73, v211, vcc
	v_cndmask_b32_e32 v72, v72, v211, vcc
	v_max3_f32 v168, v168, v70, v71
	v_cndmask_b32_e32 v75, v75, v211, vcc
	v_cndmask_b32_e32 v74, v74, v211, vcc
	v_max3_f32 v168, v168, v72, v73
	v_cndmask_b32_e32 v77, v77, v211, vcc
	v_cndmask_b32_e32 v76, v76, v211, vcc
	v_max3_f32 v168, v168, v74, v75
	v_cndmask_b32_e32 v79, v79, v211, vcc
	v_cndmask_b32_e32 v78, v78, v211, vcc
	v_max3_f32 v168, v168, v76, v77
	v_cndmask_b32_e32 v81, v81, v211, vcc
	v_cndmask_b32_e32 v80, v80, v211, vcc
	v_max3_f32 v168, v168, v78, v79
	v_cndmask_b32_e32 v83, v83, v211, vcc
	v_cndmask_b32_e32 v82, v82, v211, vcc
	v_max3_f32 v168, v168, v80, v81
	v_cndmask_b32_e32 v85, v85, v211, vcc
	v_cndmask_b32_e32 v84, v84, v211, vcc
	v_max3_f32 v168, v168, v82, v83
	v_cndmask_b32_e32 v87, v87, v211, vcc
	v_cndmask_b32_e32 v86, v86, v211, vcc
	v_max3_f32 v168, v168, v84, v85
	v_cndmask_b32_e32 v89, v89, v211, vcc
	v_cndmask_b32_e32 v88, v88, v211, vcc
	v_max3_f32 v168, v168, v86, v87
	v_cndmask_b32_e32 v91, v91, v211, vcc
	v_cndmask_b32_e32 v90, v90, v211, vcc
	v_max3_f32 v168, v168, v88, v89
	v_cndmask_b32_e32 v93, v93, v211, vcc
	v_cndmask_b32_e32 v92, v92, v211, vcc
	v_max3_f32 v168, v168, v90, v91
	v_cndmask_b32_e32 v95, v95, v211, vcc
	v_cndmask_b32_e32 v94, v94, v211, vcc
	v_max3_f32 v168, v168, v92, v93
	v_max3_f32 v168, v168, v94, v95
	v_mov_b32_e32 v169, v168
	s_nop 1
	v_permlane32_swap_b32_e32 v168, v169
	v_max_f32_e32 v169, v169, v169
	v_max_f32_e32 v168, v168, v168
	v_max_f32_e32 v168, v168, v169
	v_sub_f32_e32 v169, v168, v203
	v_cmp_ge_f32_e32 vcc, s84, v169
	v_mov_b32_e32 v177, 1.0
	s_cmp_eq_u64 vcc, exec
	s_setprio 1
	s_branch .Lpvma_join
; #define LAS __attribute__((address_space(3)))
; #define SBAR() __builtin_amdgcn_sched_barrier(0)
; #define RESC(a) do { if (__any((a) < 1.f)) { if (hi == 0) al_l[r32] = (a); asm volatile("s_waitcnt lgkmcnt(0)" ::: "memory"); \
;     _Pragma("unroll") for (int d = 0; d < 4; ++d) _Pragma("unroll") for (int r = 0; r < 16; ++r) o[d][r] *= al_l[crow(r, hi)]; } } while (0)
; template <bool BAND> DI void partialSM(f32x16& p0, f32x16& p1, float& m_reg, float& mn, float& alpha, bool masked, const LAS float* tb, float C) {
;   if (masked) {
; #pragma unroll
;     for (int r = 0; r < 16; ++r) { p0[r] = -1e30f; p1[r] = -1e30f; }
;   } else if (BAND) {
; #pragma unroll
;     for (int r = 0; r < 16; ++r) { const int ko = (r & 3) + 8 * (r >> 2); p0[r] = fmaf(p0[r], C, tb[ko]); }
;     SBAR();
; #pragma unroll
;     for (int r = 0; r < 16; ++r) { const int ko = (r & 3) + 8 * (r >> 2); p1[r] = fmaf(p1[r], C, tb[ko + 32]); }
;   }
;   const float CC = BAND ? 1.f : C;
;   const float THRP = 11.5f / CC;
;   float pmax = p0[0];
; #pragma unroll
;   for (int r = 1; r < 16; ++r) pmax = fmaxf(pmax, p0[r]);
; #pragma unroll
;   for (int r = 0; r < 16; ++r) pmax = fmaxf(pmax, p1[r]);
;   { auto rr = __builtin_amdgcn_permlane32_swap(__float_as_uint(pmax), __float_as_uint(pmax), false, false);
;     pmax = fmaxf(__uint_as_float(rr[0]), __uint_as_float(rr[1])); }
;   if (__builtin_expect(__all(pmax - m_reg <= THRP), 1)) { mn = m_reg; alpha = 1.f; }
;   else { mn = fmaxf(m_reg, pmax); alpha = __builtin_amdgcn_exp2f((m_reg - mn) * CC); m_reg = mn; }
; template <bool BAND, int SD, bool ACT> DI void attn_unit_(const Unit& U, LAS char* lds, float C) {
;     ...
;     finishSM(pA0, pA1, alA, l_reg, pa0, pa1, pa2, pa3); SBAR();
;     pv_d0(o, vb0, pa0, pa1, pa2, pa3); partialSM<BAND>(pB0, pB1, m_reg, mnB, alB, MASKED(NT - 1), T3 + jb0 + 64 * (NT - 1), C);
;   }
;   __syncthreads();
;   if (ACT) {
;     RESC(alB);
;     finishSM(pB0, pB1, alB, l_reg, pa0, pa1, pa2, pa3); SBAR();
;     pv_d0(o, vb0 + SHM_V, pa0, pa1, pa2, pa3);
.Lqsme_skip:
	s_setprio 0
	s_waitcnt lgkmcnt(0)
	v_add_f32_e32 v112, 0, v110
	v_exp_f32_e32 v114, v175
	v_exp_f32_e32 v115, v172
	v_cvt_pk_bf16_f32 v132, v110, v111
	v_add_f32_e32 v110, v111, v112
	v_add_f32_e32 v110, v108, v110
	v_cvt_pk_bf16_f32 v133, v108, v109
	v_add_f32_e32 v108, v109, v110
	v_add_f32_e32 v108, v106, v108
	v_cvt_pk_bf16_f32 v134, v106, v107
	v_add_f32_e32 v106, v107, v108
	v_add_f32_e32 v106, v72, v106
	v_add_f32_e32 v106, v73, v106
	v_add_f32_e32 v106, v66, v106
	v_add_f32_e32 v106, v67, v106
	v_add_f32_e32 v106, v64, v106
	v_add_f32_e32 v106, v65, v106
	v_exp_f32_e32 v108, v196
	v_add_f32_e32 v106, v68, v106
	v_exp_f32_e32 v109, v197
	v_add_f32_e32 v106, v69, v106
	v_exp_f32_e32 v110, v178
	v_add_f32_e32 v106, v70, v106
	v_exp_f32_e32 v111, v179
	v_add_f32_e32 v106, v71, v106
	v_exp_f32_e32 v112, v174
	v_add_f32_e32 v106, v108, v106
	v_add_f32_e32 v106, v109, v106
	v_add_f32_e32 v106, v110, v106
	v_exp_f32_e32 v128, v173
	v_add_f32_e32 v106, v111, v106
	v_exp_f32_e32 v129, v170
	v_add_f32_e32 v106, v112, v106
	v_exp_f32_e32 v130, v171
	v_add_f32_e32 v106, v114, v106
	v_exp_f32_e32 v131, v168
	v_add_f32_e32 v106, v115, v106
	v_exp_f32_e32 v136, v169
	v_add_f32_e32 v106, v128, v106
	v_exp_f32_e32 v137, v166
	v_add_f32_e32 v106, v129, v106
	v_exp_f32_e32 v138, v167
	v_add_f32_e32 v106, v130, v106
	v_exp_f32_e32 v139, v164
	v_add_f32_e32 v106, v131, v106
	v_exp_f32_e32 v140, v165
	v_add_f32_e32 v106, v136, v106
	v_add_f32_e32 v106, v137, v106
	v_add_f32_e32 v106, v138, v106
	v_add_f32_e32 v106, v139, v106
	v_add_f32_e32 v106, v140, v106
	v_mov_b32_e32 v107, v106
	v_cvt_pk_bf16_f32 v135, v72, v73
	v_cvt_pk_bf16_f32 v66, v66, v67
	v_cvt_pk_bf16_f32 v67, v64, v65
	v_cvt_pk_bf16_f32 v68, v68, v69
	v_cvt_pk_bf16_f32 v69, v70, v71
	v_permlane32_swap_b32_e32 v106, v107
	v_permlane32_swap_b32_e32 v66, v68
	v_permlane32_swap_b32_e32 v67, v69
	v_cvt_pk_bf16_f32 v108, v108, v109
	v_cvt_pk_bf16_f32 v109, v110, v111
	v_cvt_pk_bf16_f32 v110, v112, v114
	v_cvt_pk_bf16_f32 v111, v115, v128
	v_cvt_pk_bf16_f32 v120, v129, v130
	v_cvt_pk_bf16_f32 v121, v131, v136
	v_cvt_pk_bf16_f32 v122, v137, v138
	v_cvt_pk_bf16_f32 v123, v139, v140
	v_permlane32_swap_b32_e32 v132, v134
	v_permlane32_swap_b32_e32 v133, v135
	v_permlane32_swap_b32_e32 v108, v110
	v_permlane32_swap_b32_e32 v109, v111
	v_permlane32_swap_b32_e32 v120, v122
	v_permlane32_swap_b32_e32 v121, v123
	s_setprio 1
	s_branch .Lqsme_join
.Lpvme_skip:
	s_setprio 0
	s_waitcnt lgkmcnt(0)
	s_nop 0
	s_add_i32 s14, s19, -1
	s_cmp_le_i32 s19, s12
	s_cselect_b64 s[12:13], -1, 0
	s_cmp_gt_i32 s14, s21
	s_cselect_b64 s[14:15], -1, 0
	s_or_b64 vcc, s[12:13], s[14:15]
	v_cndmask_b32_e32 v74, v74, v211, vcc
	v_cndmask_b32_e32 v75, v75, v211, vcc
	v_cndmask_b32_e32 v69, v94, v211, vcc
	v_cndmask_b32_e32 v94, v95, v211, vcc
	v_max_f32_e32 v64, v75, v75
	v_max_f32_e32 v95, v74, v74
	v_cndmask_b32_e32 v76, v76, v211, vcc
	v_cndmask_b32_e32 v77, v77, v211, vcc
	v_max_f32_e32 v64, v95, v64
	v_cndmask_b32_e32 v78, v78, v211, vcc
	v_cndmask_b32_e32 v79, v79, v211, vcc
	v_max3_f32 v64, v64, v76, v77
	v_cndmask_b32_e32 v80, v80, v211, vcc
	v_cndmask_b32_e32 v81, v81, v211, vcc
	v_max3_f32 v64, v64, v78, v79
	v_cndmask_b32_e32 v82, v82, v211, vcc
	v_cndmask_b32_e32 v83, v83, v211, vcc
	v_max3_f32 v64, v64, v80, v81
	v_cndmask_b32_e32 v84, v84, v211, vcc
	v_cndmask_b32_e32 v85, v85, v211, vcc
	v_max3_f32 v64, v64, v82, v83
	v_cndmask_b32_e32 v86, v86, v211, vcc
	v_cndmask_b32_e32 v87, v87, v211, vcc
	v_max3_f32 v64, v64, v84, v85
	v_cndmask_b32_e32 v88, v88, v211, vcc
	v_cndmask_b32_e32 v89, v89, v211, vcc
	v_max3_f32 v64, v64, v86, v87
	v_cndmask_b32_e32 v90, v90, v211, vcc
	v_cndmask_b32_e32 v91, v91, v211, vcc
	v_max3_f32 v64, v64, v88, v89
	v_cndmask_b32_e32 v92, v92, v211, vcc
	v_cndmask_b32_e32 v93, v93, v211, vcc
	v_max3_f32 v64, v64, v90, v91
	v_max3_f32 v64, v64, v92, v93
	v_cndmask_b32_e32 v67, v96, v211, vcc
	v_cndmask_b32_e32 v68, v97, v211, vcc
	v_max3_f32 v64, v64, v69, v94
	v_cndmask_b32_e32 v98, v98, v211, vcc
	v_cndmask_b32_e32 v66, v99, v211, vcc
	v_max3_f32 v64, v64, v67, v68
	v_cndmask_b32_e32 v73, v100, v211, vcc
	v_cndmask_b32_e32 v100, v101, v211, vcc
	v_max3_f32 v64, v64, v98, v66
	v_cndmask_b32_e32 v72, v102, v211, vcc
	v_cndmask_b32_e32 v71, v103, v211, vcc
	v_max3_f32 v64, v64, v73, v100
	v_cndmask_b32_e32 v65, v104, v211, vcc
	v_cndmask_b32_e32 v70, v105, v211, vcc
	v_max3_f32 v64, v64, v72, v71
	v_max3_f32 v64, v64, v65, v70
	v_mov_b32_e32 v95, v64
	s_nop 1
	v_permlane32_swap_b32_e32 v64, v95
	v_max_f32_e32 v95, v95, v95
	v_max_f32_e32 v64, v64, v64
	v_max_f32_e32 v95, v64, v95
	v_sub_f32_e32 v64, v95, v203
	v_cmp_ge_f32_e32 vcc, s84, v64
	s_cmp_eq_u64 vcc, exec
	v_mov_b32_e32 v64, 1.0
	s_setprio 1
	s_branch .Lpvme_join
.Lpvmf_skip:
	s_setprio 0
	s_waitcnt lgkmcnt(0)
	s_nop 0
	s_setprio 1
	s_branch .Lpvmf_join
